# half-unit loop: both wave halves issue their LDS-DMA pieces interleaved with their MFMA block (load segments are fragment reads only)
# baseline (speedup 1.0000x reference)
.Lhu_x:
	ds_read_b128 v[150:153], v248
	ds_read_b128 v[154:157], v248 offset:1024
	ds_read_b128 v[158:161], v248 offset:2048
	ds_read_b128 v[162:165], v248 offset:3072
	ds_read_b128 v[134:137], v249
	ds_read_b128 v[138:141], v249 offset:1024
	ds_read_b128 v[142:145], v249 offset:2048
	ds_read_b128 v[146:149], v249 offset:3072
	ds_read_b128 v[166:169], v250
	ds_read_b128 v[170:173], v250 offset:1024
	ds_read_b128 v[174:177], v250 offset:2048
	ds_read_b128 v[178:181], v250 offset:3072
	ds_read_b128 v[182:185], v250 offset:4096
	ds_read_b128 v[186:189], v250 offset:5120
	ds_read_b128 v[190:193], v250 offset:6144
	ds_read_b128 v[194:197], v250 offset:7168
	s_setprio 1
	s_waitcnt lgkmcnt(0)
	s_barrier
	s_add_u32 s88, s2, 0x40000
	s_addc_u32 s89, s3, 0
	v_mfma_f32_16x16x32_bf16 v[102:105], v[150:153], v[166:169], v[102:105]
	v_mfma_f32_16x16x32_bf16 v[70:73], v[158:161], v[166:169], v[70:73]
	v_mfma_f32_16x16x32_bf16 v[114:117], v[150:153], v[174:177], v[114:117]
	v_mfma_f32_16x16x32_bf16 v[82:85], v[158:161], v[174:177], v[82:85]
	s_add_i32 m0, s61, 0xc000
	s_nop 0
	global_load_lds_dwordx4 v208, s[2:3]
	v_mfma_f32_16x16x32_bf16 v[110:113], v[150:153], v[182:185], v[110:113]
	v_mfma_f32_16x16x32_bf16 v[78:81], v[158:161], v[182:185], v[78:81]
	v_mfma_f32_16x16x32_bf16 v[106:109], v[150:153], v[190:193], v[106:109]
	v_mfma_f32_16x16x32_bf16 v[74:77], v[158:161], v[190:193], v[74:77]
	s_add_i32 m0, s61, 0xe000
	s_nop 0
	global_load_lds_dwordx4 v212, s[2:3]
	v_mfma_f32_16x16x32_bf16 v[102:105], v[154:157], v[170:173], v[102:105]
	v_mfma_f32_16x16x32_bf16 v[70:73], v[162:165], v[170:173], v[70:73]
	v_mfma_f32_16x16x32_bf16 v[114:117], v[154:157], v[178:181], v[114:117]
	v_mfma_f32_16x16x32_bf16 v[82:85], v[162:165], v[178:181], v[82:85]
	s_add_i32 m0, s61, 0x20000
	s_nop 0
	global_load_lds_dwordx4 v208, s[88:89]
	v_mfma_f32_16x16x32_bf16 v[110:113], v[154:157], v[186:189], v[110:113]
	v_mfma_f32_16x16x32_bf16 v[78:81], v[162:165], v[186:189], v[78:81]
	v_mfma_f32_16x16x32_bf16 v[106:109], v[154:157], v[194:197], v[106:109]
	v_mfma_f32_16x16x32_bf16 v[74:77], v[162:165], v[194:197], v[74:77]
	s_add_i32 m0, s61, 0x22000
	s_nop 0
	global_load_lds_dwordx4 v212, s[88:89]
	v_mfma_f32_16x16x32_bf16 v[130:133], v[134:137], v[166:169], v[130:133]
	v_mfma_f32_16x16x32_bf16 v[98:101], v[142:145], v[166:169], v[98:101]
	v_mfma_f32_16x16x32_bf16 v[126:129], v[134:137], v[174:177], v[126:129]
	v_mfma_f32_16x16x32_bf16 v[94:97], v[142:145], v[174:177], v[94:97]
	s_mov_b32 m0, s95
	s_nop 0
	global_load_lds_dwordx4 v206, s[84:85]
	v_mfma_f32_16x16x32_bf16 v[122:125], v[134:137], v[182:185], v[122:125]
	v_mfma_f32_16x16x32_bf16 v[90:93], v[142:145], v[182:185], v[90:93]
	v_mfma_f32_16x16x32_bf16 v[118:121], v[134:137], v[190:193], v[118:121]
	v_mfma_f32_16x16x32_bf16 v[86:89], v[142:145], v[190:193], v[86:89]
	s_mov_b32 m0, s96
	s_nop 0
	global_load_lds_dwordx4 v210, s[84:85]
	v_mfma_f32_16x16x32_bf16 v[130:133], v[138:141], v[170:173], v[130:133]
	v_mfma_f32_16x16x32_bf16 v[98:101], v[146:149], v[170:173], v[98:101]
	v_mfma_f32_16x16x32_bf16 v[126:129], v[138:141], v[178:181], v[126:129]
	v_mfma_f32_16x16x32_bf16 v[94:97], v[146:149], v[178:181], v[94:97]
	v_mfma_f32_16x16x32_bf16 v[122:125], v[138:141], v[186:189], v[122:125]
	v_mfma_f32_16x16x32_bf16 v[90:93], v[146:149], v[186:189], v[90:93]
	v_mfma_f32_16x16x32_bf16 v[118:121], v[138:141], v[194:197], v[118:121]
	v_mfma_f32_16x16x32_bf16 v[86:89], v[146:149], v[194:197], v[86:89]
	s_add_u32 s2, s2, 0x80
	s_addc_u32 s3, s3, 0
	s_add_u32 s84, s84, 0x80
	s_addc_u32 s85, s85, 0
	s_waitcnt vmcnt(6)
	s_barrier
	s_setprio 0
	ds_read_b128 v[150:153], v220
	ds_read_b128 v[154:157], v220 offset:1024
	ds_read_b128 v[158:161], v220 offset:2048
	ds_read_b128 v[162:165], v220 offset:3072
	ds_read_b128 v[134:137], v221
	ds_read_b128 v[138:141], v221 offset:1024
	ds_read_b128 v[142:145], v221 offset:2048
	ds_read_b128 v[146:149], v221 offset:3072
	ds_read_b128 v[166:169], v250 offset:32768
	ds_read_b128 v[170:173], v250 offset:33792
	ds_read_b128 v[174:177], v250 offset:34816
	ds_read_b128 v[178:181], v250 offset:35840
	ds_read_b128 v[182:185], v250 offset:36864
	ds_read_b128 v[186:189], v250 offset:37888
	ds_read_b128 v[190:193], v250 offset:38912
	ds_read_b128 v[194:197], v250 offset:39936
	s_setprio 1
	s_waitcnt lgkmcnt(0)
	s_barrier
	s_add_u32 s88, s2, 0x40000
	s_addc_u32 s89, s3, 0
	v_mfma_f32_16x16x32_bf16 v[102:105], v[150:153], v[166:169], v[102:105]
	v_mfma_f32_16x16x32_bf16 v[70:73], v[158:161], v[166:169], v[70:73]
	v_mfma_f32_16x16x32_bf16 v[114:117], v[150:153], v[174:177], v[114:117]
	v_mfma_f32_16x16x32_bf16 v[82:85], v[158:161], v[174:177], v[82:85]
	s_mov_b32 m0, s73
	s_nop 0
	global_load_lds_dwordx4 v208, s[2:3]
	v_mfma_f32_16x16x32_bf16 v[110:113], v[150:153], v[182:185], v[110:113]
	v_mfma_f32_16x16x32_bf16 v[78:81], v[158:161], v[182:185], v[78:81]
	v_mfma_f32_16x16x32_bf16 v[106:109], v[150:153], v[190:193], v[106:109]
	v_mfma_f32_16x16x32_bf16 v[74:77], v[158:161], v[190:193], v[74:77]
	s_mov_b32 m0, s75
	s_nop 0
	global_load_lds_dwordx4 v212, s[2:3]
	v_mfma_f32_16x16x32_bf16 v[102:105], v[154:157], v[170:173], v[102:105]
	v_mfma_f32_16x16x32_bf16 v[70:73], v[162:165], v[170:173], v[70:73]
	v_mfma_f32_16x16x32_bf16 v[114:117], v[154:157], v[178:181], v[114:117]
	v_mfma_f32_16x16x32_bf16 v[82:85], v[162:165], v[178:181], v[82:85]
	s_mov_b32 m0, s92
	s_nop 0
	global_load_lds_dwordx4 v208, s[88:89]
	v_mfma_f32_16x16x32_bf16 v[110:113], v[154:157], v[186:189], v[110:113]
	v_mfma_f32_16x16x32_bf16 v[78:81], v[162:165], v[186:189], v[78:81]
	v_mfma_f32_16x16x32_bf16 v[106:109], v[154:157], v[194:197], v[106:109]
	v_mfma_f32_16x16x32_bf16 v[74:77], v[162:165], v[194:197], v[74:77]
	s_mov_b32 m0, s93
	s_nop 0
	global_load_lds_dwordx4 v212, s[88:89]
	v_mfma_f32_16x16x32_bf16 v[130:133], v[134:137], v[166:169], v[130:133]
	v_mfma_f32_16x16x32_bf16 v[98:101], v[142:145], v[166:169], v[98:101]
	v_mfma_f32_16x16x32_bf16 v[126:129], v[134:137], v[174:177], v[126:129]
	v_mfma_f32_16x16x32_bf16 v[94:97], v[142:145], v[174:177], v[94:97]
	s_mov_b32 m0, s61
	s_nop 0
	global_load_lds_dwordx4 v206, s[84:85]
	v_mfma_f32_16x16x32_bf16 v[122:125], v[134:137], v[182:185], v[122:125]
	v_mfma_f32_16x16x32_bf16 v[90:93], v[142:145], v[182:185], v[90:93]
	v_mfma_f32_16x16x32_bf16 v[118:121], v[134:137], v[190:193], v[118:121]
	v_mfma_f32_16x16x32_bf16 v[86:89], v[142:145], v[190:193], v[86:89]
	s_mov_b32 m0, s94
	s_nop 0
	global_load_lds_dwordx4 v210, s[84:85]
	v_mfma_f32_16x16x32_bf16 v[130:133], v[138:141], v[170:173], v[130:133]
	v_mfma_f32_16x16x32_bf16 v[98:101], v[146:149], v[170:173], v[98:101]
	v_mfma_f32_16x16x32_bf16 v[126:129], v[138:141], v[178:181], v[126:129]
	v_mfma_f32_16x16x32_bf16 v[94:97], v[146:149], v[178:181], v[94:97]
	v_mfma_f32_16x16x32_bf16 v[122:125], v[138:141], v[186:189], v[122:125]
	v_mfma_f32_16x16x32_bf16 v[90:93], v[146:149], v[186:189], v[90:93]
	v_mfma_f32_16x16x32_bf16 v[118:121], v[138:141], v[194:197], v[118:121]
	v_mfma_f32_16x16x32_bf16 v[86:89], v[146:149], v[194:197], v[86:89]
	s_add_u32 s2, s2, 0x80
	s_addc_u32 s3, s3, 0
	s_add_u32 s84, s84, 0x80
	s_addc_u32 s85, s85, 0
	s_waitcnt vmcnt(6)
	s_barrier
	s_setprio 0
	ds_read_b128 v[150:153], v222
	ds_read_b128 v[154:157], v222 offset:1024
	ds_read_b128 v[158:161], v222 offset:2048
	ds_read_b128 v[162:165], v222 offset:3072
	ds_read_b128 v[134:137], v223
	ds_read_b128 v[138:141], v223 offset:1024
	ds_read_b128 v[142:145], v223 offset:2048
	ds_read_b128 v[146:149], v223 offset:3072
	ds_read_b128 v[166:169], v250 offset:16384
	ds_read_b128 v[170:173], v250 offset:17408
	ds_read_b128 v[174:177], v250 offset:18432
	ds_read_b128 v[178:181], v250 offset:19456
	ds_read_b128 v[182:185], v250 offset:20480
	ds_read_b128 v[186:189], v250 offset:21504
	ds_read_b128 v[190:193], v250 offset:22528
	ds_read_b128 v[194:197], v250 offset:23552
	s_setprio 1
	s_waitcnt lgkmcnt(0)
	s_barrier
	s_add_u32 s88, s2, 0x40000
	s_addc_u32 s89, s3, 0
	v_mfma_f32_16x16x32_bf16 v[102:105], v[150:153], v[166:169], v[102:105]
	v_mfma_f32_16x16x32_bf16 v[70:73], v[158:161], v[166:169], v[70:73]
	v_mfma_f32_16x16x32_bf16 v[114:117], v[150:153], v[174:177], v[114:117]
	v_mfma_f32_16x16x32_bf16 v[82:85], v[158:161], v[174:177], v[82:85]
	s_mov_b32 m0, s54
	s_nop 0
	global_load_lds_dwordx4 v208, s[2:3]
	v_mfma_f32_16x16x32_bf16 v[110:113], v[150:153], v[182:185], v[110:113]
	v_mfma_f32_16x16x32_bf16 v[78:81], v[158:161], v[182:185], v[78:81]
	v_mfma_f32_16x16x32_bf16 v[106:109], v[150:153], v[190:193], v[106:109]
	v_mfma_f32_16x16x32_bf16 v[74:77], v[158:161], v[190:193], v[74:77]
	s_mov_b32 m0, s55
	s_nop 0
	global_load_lds_dwordx4 v212, s[2:3]
	v_mfma_f32_16x16x32_bf16 v[102:105], v[154:157], v[170:173], v[102:105]
	v_mfma_f32_16x16x32_bf16 v[70:73], v[162:165], v[170:173], v[70:73]
	v_mfma_f32_16x16x32_bf16 v[114:117], v[154:157], v[178:181], v[114:117]
	v_mfma_f32_16x16x32_bf16 v[82:85], v[162:165], v[178:181], v[82:85]
	s_mov_b32 m0, s59
	s_nop 0
	global_load_lds_dwordx4 v208, s[88:89]
	v_mfma_f32_16x16x32_bf16 v[110:113], v[154:157], v[186:189], v[110:113]
	v_mfma_f32_16x16x32_bf16 v[78:81], v[162:165], v[186:189], v[78:81]
	v_mfma_f32_16x16x32_bf16 v[106:109], v[154:157], v[194:197], v[106:109]
	v_mfma_f32_16x16x32_bf16 v[74:77], v[162:165], v[194:197], v[74:77]
	s_mov_b32 m0, s24
	s_nop 0
	global_load_lds_dwordx4 v212, s[88:89]
	v_mfma_f32_16x16x32_bf16 v[130:133], v[134:137], v[166:169], v[130:133]
	v_mfma_f32_16x16x32_bf16 v[98:101], v[142:145], v[166:169], v[98:101]
	v_mfma_f32_16x16x32_bf16 v[126:129], v[134:137], v[174:177], v[126:129]
	v_mfma_f32_16x16x32_bf16 v[94:97], v[142:145], v[174:177], v[94:97]
	s_mov_b32 m0, s57
	s_nop 0
	global_load_lds_dwordx4 v206, s[84:85]
	v_mfma_f32_16x16x32_bf16 v[122:125], v[134:137], v[182:185], v[122:125]
	v_mfma_f32_16x16x32_bf16 v[90:93], v[142:145], v[182:185], v[90:93]
	v_mfma_f32_16x16x32_bf16 v[118:121], v[134:137], v[190:193], v[118:121]
	v_mfma_f32_16x16x32_bf16 v[86:89], v[142:145], v[190:193], v[86:89]
	s_mov_b32 m0, s58
	s_nop 0
	global_load_lds_dwordx4 v210, s[84:85]
	v_mfma_f32_16x16x32_bf16 v[130:133], v[138:141], v[170:173], v[130:133]
	v_mfma_f32_16x16x32_bf16 v[98:101], v[146:149], v[170:173], v[98:101]
	v_mfma_f32_16x16x32_bf16 v[126:129], v[138:141], v[178:181], v[126:129]
	v_mfma_f32_16x16x32_bf16 v[94:97], v[146:149], v[178:181], v[94:97]
	v_mfma_f32_16x16x32_bf16 v[122:125], v[138:141], v[186:189], v[122:125]
	v_mfma_f32_16x16x32_bf16 v[90:93], v[146:149], v[186:189], v[90:93]
	v_mfma_f32_16x16x32_bf16 v[118:121], v[138:141], v[194:197], v[118:121]
	v_mfma_f32_16x16x32_bf16 v[86:89], v[146:149], v[194:197], v[86:89]
	s_add_u32 s2, s2, 0x80
	s_addc_u32 s3, s3, 0
	s_add_u32 s84, s84, 0x80
	s_addc_u32 s85, s85, 0
	s_waitcnt vmcnt(6)
	s_barrier
	s_setprio 0
	s_add_i32 s45, s45, 1
	s_cmp_lt_u32 s45, 4
	s_cbranch_scc1 .Lhu_x
	ds_read_b128 v[150:153], v248
	ds_read_b128 v[154:157], v248 offset:1024
	ds_read_b128 v[158:161], v248 offset:2048
	ds_read_b128 v[162:165], v248 offset:3072
	ds_read_b128 v[134:137], v249
	ds_read_b128 v[138:141], v249 offset:1024
	ds_read_b128 v[142:145], v249 offset:2048
	ds_read_b128 v[146:149], v249 offset:3072
	ds_read_b128 v[166:169], v250
	ds_read_b128 v[170:173], v250 offset:1024
	ds_read_b128 v[174:177], v250 offset:2048
	ds_read_b128 v[178:181], v250 offset:3072
	ds_read_b128 v[182:185], v250 offset:4096
	ds_read_b128 v[186:189], v250 offset:5120
	ds_read_b128 v[190:193], v250 offset:6144
	ds_read_b128 v[194:197], v250 offset:7168
	s_setprio 1
	s_waitcnt lgkmcnt(0)
	s_barrier
	s_add_u32 s88, s2, 0x40000
	s_addc_u32 s89, s3, 0
	v_mfma_f32_16x16x32_bf16 v[102:105], v[150:153], v[166:169], v[102:105]
	v_mfma_f32_16x16x32_bf16 v[70:73], v[158:161], v[166:169], v[70:73]
	v_mfma_f32_16x16x32_bf16 v[114:117], v[150:153], v[174:177], v[114:117]
	v_mfma_f32_16x16x32_bf16 v[82:85], v[158:161], v[174:177], v[82:85]
	s_add_i32 m0, s61, 0xc000
	s_nop 0
	global_load_lds_dwordx4 v208, s[2:3]
	v_mfma_f32_16x16x32_bf16 v[110:113], v[150:153], v[182:185], v[110:113]
	v_mfma_f32_16x16x32_bf16 v[78:81], v[158:161], v[182:185], v[78:81]
	v_mfma_f32_16x16x32_bf16 v[106:109], v[150:153], v[190:193], v[106:109]
	v_mfma_f32_16x16x32_bf16 v[74:77], v[158:161], v[190:193], v[74:77]
	s_add_i32 m0, s61, 0xe000
	s_nop 0
	global_load_lds_dwordx4 v212, s[2:3]
	v_mfma_f32_16x16x32_bf16 v[102:105], v[154:157], v[170:173], v[102:105]
	v_mfma_f32_16x16x32_bf16 v[70:73], v[162:165], v[170:173], v[70:73]
	v_mfma_f32_16x16x32_bf16 v[114:117], v[154:157], v[178:181], v[114:117]
	v_mfma_f32_16x16x32_bf16 v[82:85], v[162:165], v[178:181], v[82:85]
	s_add_i32 m0, s61, 0x20000
	s_nop 0
	global_load_lds_dwordx4 v208, s[88:89]
	v_mfma_f32_16x16x32_bf16 v[110:113], v[154:157], v[186:189], v[110:113]
	v_mfma_f32_16x16x32_bf16 v[78:81], v[162:165], v[186:189], v[78:81]
	v_mfma_f32_16x16x32_bf16 v[106:109], v[154:157], v[194:197], v[106:109]
	v_mfma_f32_16x16x32_bf16 v[74:77], v[162:165], v[194:197], v[74:77]
	s_add_i32 m0, s61, 0x22000
	s_nop 0
	global_load_lds_dwordx4 v212, s[88:89]
	v_mfma_f32_16x16x32_bf16 v[130:133], v[134:137], v[166:169], v[130:133]
	v_mfma_f32_16x16x32_bf16 v[98:101], v[142:145], v[166:169], v[98:101]
	v_mfma_f32_16x16x32_bf16 v[126:129], v[134:137], v[174:177], v[126:129]
	v_mfma_f32_16x16x32_bf16 v[94:97], v[142:145], v[174:177], v[94:97]
	s_mov_b32 m0, s95
	s_nop 0
	global_load_lds_dwordx4 v206, s[84:85]
	v_mfma_f32_16x16x32_bf16 v[122:125], v[134:137], v[182:185], v[122:125]
	v_mfma_f32_16x16x32_bf16 v[90:93], v[142:145], v[182:185], v[90:93]
	v_mfma_f32_16x16x32_bf16 v[118:121], v[134:137], v[190:193], v[118:121]
	v_mfma_f32_16x16x32_bf16 v[86:89], v[142:145], v[190:193], v[86:89]
	s_mov_b32 m0, s96
	s_nop 0
	global_load_lds_dwordx4 v210, s[84:85]
	v_mfma_f32_16x16x32_bf16 v[130:133], v[138:141], v[170:173], v[130:133]
	v_mfma_f32_16x16x32_bf16 v[98:101], v[146:149], v[170:173], v[98:101]
	v_mfma_f32_16x16x32_bf16 v[126:129], v[138:141], v[178:181], v[126:129]
	v_mfma_f32_16x16x32_bf16 v[94:97], v[146:149], v[178:181], v[94:97]
	v_mfma_f32_16x16x32_bf16 v[122:125], v[138:141], v[186:189], v[122:125]
	v_mfma_f32_16x16x32_bf16 v[90:93], v[146:149], v[186:189], v[90:93]
	v_mfma_f32_16x16x32_bf16 v[118:121], v[138:141], v[194:197], v[118:121]
	v_mfma_f32_16x16x32_bf16 v[86:89], v[146:149], v[194:197], v[86:89]
	s_add_u32 s2, s2, 0x80
	s_addc_u32 s3, s3, 0
	s_add_u32 s84, s84, 0x80
	s_addc_u32 s85, s85, 0
	s_waitcnt vmcnt(6)
	s_barrier
	s_setprio 0
	ds_read_b128 v[150:153], v220
	ds_read_b128 v[154:157], v220 offset:1024
	ds_read_b128 v[158:161], v220 offset:2048
	ds_read_b128 v[162:165], v220 offset:3072
	ds_read_b128 v[134:137], v221
	ds_read_b128 v[138:141], v221 offset:1024
	ds_read_b128 v[142:145], v221 offset:2048
	ds_read_b128 v[146:149], v221 offset:3072
	ds_read_b128 v[166:169], v250 offset:32768
	ds_read_b128 v[170:173], v250 offset:33792
	ds_read_b128 v[174:177], v250 offset:34816
	ds_read_b128 v[178:181], v250 offset:35840
	ds_read_b128 v[182:185], v250 offset:36864
	ds_read_b128 v[186:189], v250 offset:37888
	ds_read_b128 v[190:193], v250 offset:38912
	ds_read_b128 v[194:197], v250 offset:39936
	s_setprio 1
	s_waitcnt lgkmcnt(0)
	s_barrier
	s_add_u32 s88, s2, 0x40000
	s_addc_u32 s89, s3, 0
	v_mfma_f32_16x16x32_bf16 v[102:105], v[150:153], v[166:169], v[102:105]
	v_mfma_f32_16x16x32_bf16 v[70:73], v[158:161], v[166:169], v[70:73]
	v_mfma_f32_16x16x32_bf16 v[114:117], v[150:153], v[174:177], v[114:117]
	v_mfma_f32_16x16x32_bf16 v[82:85], v[158:161], v[174:177], v[82:85]
	s_mov_b32 m0, s73
	s_nop 0
	global_load_lds_dwordx4 v208, s[2:3]
	v_mfma_f32_16x16x32_bf16 v[110:113], v[150:153], v[182:185], v[110:113]
	v_mfma_f32_16x16x32_bf16 v[78:81], v[158:161], v[182:185], v[78:81]
	v_mfma_f32_16x16x32_bf16 v[106:109], v[150:153], v[190:193], v[106:109]
	v_mfma_f32_16x16x32_bf16 v[74:77], v[158:161], v[190:193], v[74:77]
	s_mov_b32 m0, s75
	s_nop 0
	global_load_lds_dwordx4 v212, s[2:3]
	v_mfma_f32_16x16x32_bf16 v[102:105], v[154:157], v[170:173], v[102:105]
	v_mfma_f32_16x16x32_bf16 v[70:73], v[162:165], v[170:173], v[70:73]
	v_mfma_f32_16x16x32_bf16 v[114:117], v[154:157], v[178:181], v[114:117]
	v_mfma_f32_16x16x32_bf16 v[82:85], v[162:165], v[178:181], v[82:85]
	s_mov_b32 m0, s92
	s_nop 0
	global_load_lds_dwordx4 v208, s[88:89]
	v_mfma_f32_16x16x32_bf16 v[110:113], v[154:157], v[186:189], v[110:113]
	v_mfma_f32_16x16x32_bf16 v[78:81], v[162:165], v[186:189], v[78:81]
	v_mfma_f32_16x16x32_bf16 v[106:109], v[154:157], v[194:197], v[106:109]
	v_mfma_f32_16x16x32_bf16 v[74:77], v[162:165], v[194:197], v[74:77]
	s_mov_b32 m0, s93
	s_nop 0
	global_load_lds_dwordx4 v212, s[88:89]
	v_mfma_f32_16x16x32_bf16 v[130:133], v[134:137], v[166:169], v[130:133]
	v_mfma_f32_16x16x32_bf16 v[98:101], v[142:145], v[166:169], v[98:101]
	v_mfma_f32_16x16x32_bf16 v[126:129], v[134:137], v[174:177], v[126:129]
	v_mfma_f32_16x16x32_bf16 v[94:97], v[142:145], v[174:177], v[94:97]
	s_mov_b32 m0, s61
	s_nop 0
	global_load_lds_dwordx4 v206, s[84:85]
	v_mfma_f32_16x16x32_bf16 v[122:125], v[134:137], v[182:185], v[122:125]
	v_mfma_f32_16x16x32_bf16 v[90:93], v[142:145], v[182:185], v[90:93]
	v_mfma_f32_16x16x32_bf16 v[118:121], v[134:137], v[190:193], v[118:121]
	v_mfma_f32_16x16x32_bf16 v[86:89], v[142:145], v[190:193], v[86:89]
	s_mov_b32 m0, s94
	s_nop 0
	global_load_lds_dwordx4 v210, s[84:85]
	v_mfma_f32_16x16x32_bf16 v[130:133], v[138:141], v[170:173], v[130:133]
	v_mfma_f32_16x16x32_bf16 v[98:101], v[146:149], v[170:173], v[98:101]
	v_mfma_f32_16x16x32_bf16 v[126:129], v[138:141], v[178:181], v[126:129]
	v_mfma_f32_16x16x32_bf16 v[94:97], v[146:149], v[178:181], v[94:97]
	v_mfma_f32_16x16x32_bf16 v[122:125], v[138:141], v[186:189], v[122:125]
	v_mfma_f32_16x16x32_bf16 v[90:93], v[146:149], v[186:189], v[90:93]
	v_mfma_f32_16x16x32_bf16 v[118:121], v[138:141], v[194:197], v[118:121]
	v_mfma_f32_16x16x32_bf16 v[86:89], v[146:149], v[194:197], v[86:89]
	s_add_u32 s2, s2, 0x80
	s_addc_u32 s3, s3, 0
	s_add_u32 s84, s84, 0x80
	s_addc_u32 s85, s85, 0
	s_waitcnt vmcnt(6)
	s_barrier
	s_setprio 0
	ds_read_b128 v[150:153], v222
	ds_read_b128 v[154:157], v222 offset:1024
	ds_read_b128 v[158:161], v222 offset:2048
	ds_read_b128 v[162:165], v222 offset:3072
	ds_read_b128 v[134:137], v223
	ds_read_b128 v[138:141], v223 offset:1024
	ds_read_b128 v[142:145], v223 offset:2048
	ds_read_b128 v[146:149], v223 offset:3072
	ds_read_b128 v[166:169], v250 offset:16384
	ds_read_b128 v[170:173], v250 offset:17408
	ds_read_b128 v[174:177], v250 offset:18432
	ds_read_b128 v[178:181], v250 offset:19456
	ds_read_b128 v[182:185], v250 offset:20480
	ds_read_b128 v[186:189], v250 offset:21504
	ds_read_b128 v[190:193], v250 offset:22528
	ds_read_b128 v[194:197], v250 offset:23552
	s_setprio 1
	s_waitcnt lgkmcnt(0)
	s_barrier
	v_mfma_f32_16x16x32_bf16 v[102:105], v[150:153], v[166:169], v[102:105]
	v_mfma_f32_16x16x32_bf16 v[70:73], v[158:161], v[166:169], v[70:73]
	v_mfma_f32_16x16x32_bf16 v[114:117], v[150:153], v[174:177], v[114:117]
	v_mfma_f32_16x16x32_bf16 v[82:85], v[158:161], v[174:177], v[82:85]
	v_mfma_f32_16x16x32_bf16 v[110:113], v[150:153], v[182:185], v[110:113]
	v_mfma_f32_16x16x32_bf16 v[78:81], v[158:161], v[182:185], v[78:81]
	v_mfma_f32_16x16x32_bf16 v[106:109], v[150:153], v[190:193], v[106:109]
	v_mfma_f32_16x16x32_bf16 v[74:77], v[158:161], v[190:193], v[74:77]
	v_mfma_f32_16x16x32_bf16 v[102:105], v[154:157], v[170:173], v[102:105]
	v_mfma_f32_16x16x32_bf16 v[70:73], v[162:165], v[170:173], v[70:73]
	v_mfma_f32_16x16x32_bf16 v[114:117], v[154:157], v[178:181], v[114:117]
	v_mfma_f32_16x16x32_bf16 v[82:85], v[162:165], v[178:181], v[82:85]
	v_mfma_f32_16x16x32_bf16 v[110:113], v[154:157], v[186:189], v[110:113]
	v_mfma_f32_16x16x32_bf16 v[78:81], v[162:165], v[186:189], v[78:81]
	v_mfma_f32_16x16x32_bf16 v[106:109], v[154:157], v[194:197], v[106:109]
	v_mfma_f32_16x16x32_bf16 v[74:77], v[162:165], v[194:197], v[74:77]
	v_mfma_f32_16x16x32_bf16 v[130:133], v[134:137], v[166:169], v[130:133]
	v_mfma_f32_16x16x32_bf16 v[98:101], v[142:145], v[166:169], v[98:101]
	v_mfma_f32_16x16x32_bf16 v[126:129], v[134:137], v[174:177], v[126:129]
	v_mfma_f32_16x16x32_bf16 v[94:97], v[142:145], v[174:177], v[94:97]
	v_mfma_f32_16x16x32_bf16 v[122:125], v[134:137], v[182:185], v[122:125]
	v_mfma_f32_16x16x32_bf16 v[90:93], v[142:145], v[182:185], v[90:93]
	v_mfma_f32_16x16x32_bf16 v[118:121], v[134:137], v[190:193], v[118:121]
	v_mfma_f32_16x16x32_bf16 v[86:89], v[142:145], v[190:193], v[86:89]
	v_mfma_f32_16x16x32_bf16 v[130:133], v[138:141], v[170:173], v[130:133]
	v_mfma_f32_16x16x32_bf16 v[98:101], v[146:149], v[170:173], v[98:101]
	v_mfma_f32_16x16x32_bf16 v[126:129], v[138:141], v[178:181], v[126:129]
	v_mfma_f32_16x16x32_bf16 v[94:97], v[146:149], v[178:181], v[94:97]
	v_mfma_f32_16x16x32_bf16 v[122:125], v[138:141], v[186:189], v[122:125]
	v_mfma_f32_16x16x32_bf16 v[90:93], v[146:149], v[186:189], v[90:93]
	v_mfma_f32_16x16x32_bf16 v[118:121], v[138:141], v[194:197], v[118:121]
	v_mfma_f32_16x16x32_bf16 v[86:89], v[146:149], v[194:197], v[86:89]
	s_waitcnt vmcnt(0)
	s_barrier
	s_setprio 0
	ds_read_b128 v[150:153], v248
	ds_read_b128 v[154:157], v248 offset:1024
	ds_read_b128 v[158:161], v248 offset:2048
	ds_read_b128 v[162:165], v248 offset:3072
	ds_read_b128 v[134:137], v249
	ds_read_b128 v[138:141], v249 offset:1024
	ds_read_b128 v[142:145], v249 offset:2048
	ds_read_b128 v[146:149], v249 offset:3072
	ds_read_b128 v[166:169], v250
	ds_read_b128 v[170:173], v250 offset:1024
	ds_read_b128 v[174:177], v250 offset:2048
	ds_read_b128 v[178:181], v250 offset:3072
	ds_read_b128 v[182:185], v250 offset:4096
	ds_read_b128 v[186:189], v250 offset:5120
	ds_read_b128 v[190:193], v250 offset:6144
	ds_read_b128 v[194:197], v250 offset:7168
	s_setprio 1
	s_waitcnt lgkmcnt(0)
	s_barrier
	v_mfma_f32_16x16x32_bf16 v[102:105], v[150:153], v[166:169], v[102:105]
	v_mfma_f32_16x16x32_bf16 v[70:73], v[158:161], v[166:169], v[70:73]
	v_mfma_f32_16x16x32_bf16 v[114:117], v[150:153], v[174:177], v[114:117]
	v_mfma_f32_16x16x32_bf16 v[82:85], v[158:161], v[174:177], v[82:85]
	v_mfma_f32_16x16x32_bf16 v[110:113], v[150:153], v[182:185], v[110:113]
	v_mfma_f32_16x16x32_bf16 v[78:81], v[158:161], v[182:185], v[78:81]
	v_mfma_f32_16x16x32_bf16 v[106:109], v[150:153], v[190:193], v[106:109]
	v_mfma_f32_16x16x32_bf16 v[74:77], v[158:161], v[190:193], v[74:77]
	v_mfma_f32_16x16x32_bf16 v[102:105], v[154:157], v[170:173], v[102:105]
	v_mfma_f32_16x16x32_bf16 v[70:73], v[162:165], v[170:173], v[70:73]
	v_mfma_f32_16x16x32_bf16 v[114:117], v[154:157], v[178:181], v[114:117]
	v_mfma_f32_16x16x32_bf16 v[82:85], v[162:165], v[178:181], v[82:85]
	v_mfma_f32_16x16x32_bf16 v[110:113], v[154:157], v[186:189], v[110:113]
	v_mfma_f32_16x16x32_bf16 v[78:81], v[162:165], v[186:189], v[78:81]
	v_mfma_f32_16x16x32_bf16 v[106:109], v[154:157], v[194:197], v[106:109]
	v_mfma_f32_16x16x32_bf16 v[74:77], v[162:165], v[194:197], v[74:77]
	v_mfma_f32_16x16x32_bf16 v[130:133], v[134:137], v[166:169], v[130:133]
	v_mfma_f32_16x16x32_bf16 v[98:101], v[142:145], v[166:169], v[98:101]
	v_mfma_f32_16x16x32_bf16 v[126:129], v[134:137], v[174:177], v[126:129]
	v_mfma_f32_16x16x32_bf16 v[94:97], v[142:145], v[174:177], v[94:97]
	v_mfma_f32_16x16x32_bf16 v[122:125], v[134:137], v[182:185], v[122:125]
	v_mfma_f32_16x16x32_bf16 v[90:93], v[142:145], v[182:185], v[90:93]
	v_mfma_f32_16x16x32_bf16 v[118:121], v[134:137], v[190:193], v[118:121]
	v_mfma_f32_16x16x32_bf16 v[86:89], v[142:145], v[190:193], v[86:89]
	v_mfma_f32_16x16x32_bf16 v[130:133], v[138:141], v[170:173], v[130:133]
	v_mfma_f32_16x16x32_bf16 v[98:101], v[146:149], v[170:173], v[98:101]
	v_mfma_f32_16x16x32_bf16 v[126:129], v[138:141], v[178:181], v[126:129]
	v_mfma_f32_16x16x32_bf16 v[94:97], v[146:149], v[178:181], v[94:97]
	v_mfma_f32_16x16x32_bf16 v[122:125], v[138:141], v[186:189], v[122:125]
	v_mfma_f32_16x16x32_bf16 v[90:93], v[146:149], v[186:189], v[90:93]
	v_mfma_f32_16x16x32_bf16 v[118:121], v[138:141], v[194:197], v[118:121]
	v_mfma_f32_16x16x32_bf16 v[86:89], v[146:149], v[194:197], v[86:89]
	s_waitcnt vmcnt(0)
	s_barrier
	s_setprio 0
	s_mov_b64 s[0:1], -1
	s_branch .LBB0_122

.Lhu_yl:
	ds_read_b128 v[150:153], v248
	ds_read_b128 v[154:157], v248 offset:1024
	ds_read_b128 v[158:161], v248 offset:2048
	ds_read_b128 v[162:165], v248 offset:3072
	ds_read_b128 v[134:137], v249
	ds_read_b128 v[138:141], v249 offset:1024
	ds_read_b128 v[142:145], v249 offset:2048
	ds_read_b128 v[146:149], v249 offset:3072
	ds_read_b128 v[166:169], v250
	ds_read_b128 v[170:173], v250 offset:1024
	ds_read_b128 v[174:177], v250 offset:2048
	ds_read_b128 v[178:181], v250 offset:3072
	ds_read_b128 v[182:185], v250 offset:4096
	ds_read_b128 v[186:189], v250 offset:5120
	ds_read_b128 v[190:193], v250 offset:6144
	ds_read_b128 v[194:197], v250 offset:7168
	s_setprio 1
	s_waitcnt vmcnt(6) lgkmcnt(0)
	s_barrier
	s_add_u32 s88, s2, 0x40000
	s_addc_u32 s89, s3, 0
	v_mfma_f32_16x16x32_bf16 v[102:105], v[150:153], v[166:169], v[102:105]
	v_mfma_f32_16x16x32_bf16 v[70:73], v[158:161], v[166:169], v[70:73]
	v_mfma_f32_16x16x32_bf16 v[114:117], v[150:153], v[174:177], v[114:117]
	v_mfma_f32_16x16x32_bf16 v[82:85], v[158:161], v[174:177], v[82:85]
	s_mov_b32 m0, s73
	s_nop 0
	global_load_lds_dwordx4 v208, s[2:3]
	v_mfma_f32_16x16x32_bf16 v[110:113], v[150:153], v[182:185], v[110:113]
	v_mfma_f32_16x16x32_bf16 v[78:81], v[158:161], v[182:185], v[78:81]
	v_mfma_f32_16x16x32_bf16 v[106:109], v[150:153], v[190:193], v[106:109]
	v_mfma_f32_16x16x32_bf16 v[74:77], v[158:161], v[190:193], v[74:77]
	s_mov_b32 m0, s75
	s_nop 0
	global_load_lds_dwordx4 v212, s[2:3]
	v_mfma_f32_16x16x32_bf16 v[102:105], v[154:157], v[170:173], v[102:105]
	v_mfma_f32_16x16x32_bf16 v[70:73], v[162:165], v[170:173], v[70:73]
	v_mfma_f32_16x16x32_bf16 v[114:117], v[154:157], v[178:181], v[114:117]
	v_mfma_f32_16x16x32_bf16 v[82:85], v[162:165], v[178:181], v[82:85]
	s_mov_b32 m0, s92
	s_nop 0
	global_load_lds_dwordx4 v208, s[88:89]
	v_mfma_f32_16x16x32_bf16 v[110:113], v[154:157], v[186:189], v[110:113]
	v_mfma_f32_16x16x32_bf16 v[78:81], v[162:165], v[186:189], v[78:81]
	v_mfma_f32_16x16x32_bf16 v[106:109], v[154:157], v[194:197], v[106:109]
	v_mfma_f32_16x16x32_bf16 v[74:77], v[162:165], v[194:197], v[74:77]
	s_mov_b32 m0, s93
	s_nop 0
	global_load_lds_dwordx4 v212, s[88:89]
	v_mfma_f32_16x16x32_bf16 v[130:133], v[134:137], v[166:169], v[130:133]
	v_mfma_f32_16x16x32_bf16 v[98:101], v[142:145], v[166:169], v[98:101]
	v_mfma_f32_16x16x32_bf16 v[126:129], v[134:137], v[174:177], v[126:129]
	v_mfma_f32_16x16x32_bf16 v[94:97], v[142:145], v[174:177], v[94:97]
	s_mov_b32 m0, s61
	s_nop 0
	global_load_lds_dwordx4 v206, s[84:85]
	v_mfma_f32_16x16x32_bf16 v[122:125], v[134:137], v[182:185], v[122:125]
	v_mfma_f32_16x16x32_bf16 v[90:93], v[142:145], v[182:185], v[90:93]
	v_mfma_f32_16x16x32_bf16 v[118:121], v[134:137], v[190:193], v[118:121]
	v_mfma_f32_16x16x32_bf16 v[86:89], v[142:145], v[190:193], v[86:89]
	s_mov_b32 m0, s94
	s_nop 0
	global_load_lds_dwordx4 v210, s[84:85]
	v_mfma_f32_16x16x32_bf16 v[130:133], v[138:141], v[170:173], v[130:133]
	v_mfma_f32_16x16x32_bf16 v[98:101], v[146:149], v[170:173], v[98:101]
	v_mfma_f32_16x16x32_bf16 v[126:129], v[138:141], v[178:181], v[126:129]
	v_mfma_f32_16x16x32_bf16 v[94:97], v[146:149], v[178:181], v[94:97]
	v_mfma_f32_16x16x32_bf16 v[122:125], v[138:141], v[186:189], v[122:125]
	v_mfma_f32_16x16x32_bf16 v[90:93], v[146:149], v[186:189], v[90:93]
	v_mfma_f32_16x16x32_bf16 v[118:121], v[138:141], v[194:197], v[118:121]
	v_mfma_f32_16x16x32_bf16 v[86:89], v[146:149], v[194:197], v[86:89]
	s_add_u32 s2, s2, 0x80
	s_addc_u32 s3, s3, 0
	s_add_u32 s84, s84, 0x80
	s_addc_u32 s85, s85, 0
	s_barrier
	s_setprio 0
	ds_read_b128 v[150:153], v220
	ds_read_b128 v[154:157], v220 offset:1024
	ds_read_b128 v[158:161], v220 offset:2048
	ds_read_b128 v[162:165], v220 offset:3072
	ds_read_b128 v[134:137], v221
	ds_read_b128 v[138:141], v221 offset:1024
	ds_read_b128 v[142:145], v221 offset:2048
	ds_read_b128 v[146:149], v221 offset:3072
	ds_read_b128 v[166:169], v250 offset:32768
	ds_read_b128 v[170:173], v250 offset:33792
	ds_read_b128 v[174:177], v250 offset:34816
	ds_read_b128 v[178:181], v250 offset:35840
	ds_read_b128 v[182:185], v250 offset:36864
	ds_read_b128 v[186:189], v250 offset:37888
	ds_read_b128 v[190:193], v250 offset:38912
	ds_read_b128 v[194:197], v250 offset:39936
	s_setprio 1
	s_waitcnt vmcnt(6) lgkmcnt(0)
	s_barrier
	s_add_u32 s88, s2, 0x40000
	s_addc_u32 s89, s3, 0
	v_mfma_f32_16x16x32_bf16 v[102:105], v[150:153], v[166:169], v[102:105]
	v_mfma_f32_16x16x32_bf16 v[70:73], v[158:161], v[166:169], v[70:73]
	v_mfma_f32_16x16x32_bf16 v[114:117], v[150:153], v[174:177], v[114:117]
	v_mfma_f32_16x16x32_bf16 v[82:85], v[158:161], v[174:177], v[82:85]
	s_mov_b32 m0, s54
	s_nop 0
	global_load_lds_dwordx4 v208, s[2:3]
	v_mfma_f32_16x16x32_bf16 v[110:113], v[150:153], v[182:185], v[110:113]
	v_mfma_f32_16x16x32_bf16 v[78:81], v[158:161], v[182:185], v[78:81]
	v_mfma_f32_16x16x32_bf16 v[106:109], v[150:153], v[190:193], v[106:109]
	v_mfma_f32_16x16x32_bf16 v[74:77], v[158:161], v[190:193], v[74:77]
	s_mov_b32 m0, s55
	s_nop 0
	global_load_lds_dwordx4 v212, s[2:3]
	v_mfma_f32_16x16x32_bf16 v[102:105], v[154:157], v[170:173], v[102:105]
	v_mfma_f32_16x16x32_bf16 v[70:73], v[162:165], v[170:173], v[70:73]
	v_mfma_f32_16x16x32_bf16 v[114:117], v[154:157], v[178:181], v[114:117]
	v_mfma_f32_16x16x32_bf16 v[82:85], v[162:165], v[178:181], v[82:85]
	s_mov_b32 m0, s59
	s_nop 0
	global_load_lds_dwordx4 v208, s[88:89]
	v_mfma_f32_16x16x32_bf16 v[110:113], v[154:157], v[186:189], v[110:113]
	v_mfma_f32_16x16x32_bf16 v[78:81], v[162:165], v[186:189], v[78:81]
	v_mfma_f32_16x16x32_bf16 v[106:109], v[154:157], v[194:197], v[106:109]
	v_mfma_f32_16x16x32_bf16 v[74:77], v[162:165], v[194:197], v[74:77]
	s_mov_b32 m0, s24
	s_nop 0
	global_load_lds_dwordx4 v212, s[88:89]
	v_mfma_f32_16x16x32_bf16 v[130:133], v[134:137], v[166:169], v[130:133]
	v_mfma_f32_16x16x32_bf16 v[98:101], v[142:145], v[166:169], v[98:101]
	v_mfma_f32_16x16x32_bf16 v[126:129], v[134:137], v[174:177], v[126:129]
	v_mfma_f32_16x16x32_bf16 v[94:97], v[142:145], v[174:177], v[94:97]
	s_mov_b32 m0, s57
	s_nop 0
	global_load_lds_dwordx4 v206, s[84:85]
	v_mfma_f32_16x16x32_bf16 v[122:125], v[134:137], v[182:185], v[122:125]
	v_mfma_f32_16x16x32_bf16 v[90:93], v[142:145], v[182:185], v[90:93]
	v_mfma_f32_16x16x32_bf16 v[118:121], v[134:137], v[190:193], v[118:121]
	v_mfma_f32_16x16x32_bf16 v[86:89], v[142:145], v[190:193], v[86:89]
	s_mov_b32 m0, s58
	s_nop 0
	global_load_lds_dwordx4 v210, s[84:85]
	v_mfma_f32_16x16x32_bf16 v[130:133], v[138:141], v[170:173], v[130:133]
	v_mfma_f32_16x16x32_bf16 v[98:101], v[146:149], v[170:173], v[98:101]
	v_mfma_f32_16x16x32_bf16 v[126:129], v[138:141], v[178:181], v[126:129]
	v_mfma_f32_16x16x32_bf16 v[94:97], v[146:149], v[178:181], v[94:97]
	v_mfma_f32_16x16x32_bf16 v[122:125], v[138:141], v[186:189], v[122:125]
	v_mfma_f32_16x16x32_bf16 v[90:93], v[146:149], v[186:189], v[90:93]
	v_mfma_f32_16x16x32_bf16 v[118:121], v[138:141], v[194:197], v[118:121]
	v_mfma_f32_16x16x32_bf16 v[86:89], v[146:149], v[194:197], v[86:89]
	s_add_u32 s2, s2, 0x80
	s_addc_u32 s3, s3, 0
	s_add_u32 s84, s84, 0x80
	s_addc_u32 s85, s85, 0
	s_barrier
	s_setprio 0
	ds_read_b128 v[150:153], v222
	ds_read_b128 v[154:157], v222 offset:1024
	ds_read_b128 v[158:161], v222 offset:2048
	ds_read_b128 v[162:165], v222 offset:3072
	ds_read_b128 v[134:137], v223
	ds_read_b128 v[138:141], v223 offset:1024
	ds_read_b128 v[142:145], v223 offset:2048
	ds_read_b128 v[146:149], v223 offset:3072
	ds_read_b128 v[166:169], v250 offset:16384
	ds_read_b128 v[170:173], v250 offset:17408
	ds_read_b128 v[174:177], v250 offset:18432
	ds_read_b128 v[178:181], v250 offset:19456
	ds_read_b128 v[182:185], v250 offset:20480
	ds_read_b128 v[186:189], v250 offset:21504
	ds_read_b128 v[190:193], v250 offset:22528
	ds_read_b128 v[194:197], v250 offset:23552
	s_setprio 1
	s_waitcnt vmcnt(6) lgkmcnt(0)
	s_barrier
	s_add_u32 s88, s2, 0x40000
	s_addc_u32 s89, s3, 0
	v_mfma_f32_16x16x32_bf16 v[102:105], v[150:153], v[166:169], v[102:105]
	v_mfma_f32_16x16x32_bf16 v[70:73], v[158:161], v[166:169], v[70:73]
	v_mfma_f32_16x16x32_bf16 v[114:117], v[150:153], v[174:177], v[114:117]
	v_mfma_f32_16x16x32_bf16 v[82:85], v[158:161], v[174:177], v[82:85]
	s_add_i32 m0, s61, 0xc000
	s_nop 0
	global_load_lds_dwordx4 v208, s[2:3]
	v_mfma_f32_16x16x32_bf16 v[110:113], v[150:153], v[182:185], v[110:113]
	v_mfma_f32_16x16x32_bf16 v[78:81], v[158:161], v[182:185], v[78:81]
	v_mfma_f32_16x16x32_bf16 v[106:109], v[150:153], v[190:193], v[106:109]
	v_mfma_f32_16x16x32_bf16 v[74:77], v[158:161], v[190:193], v[74:77]
	s_add_i32 m0, s61, 0xe000
	s_nop 0
	global_load_lds_dwordx4 v212, s[2:3]
	v_mfma_f32_16x16x32_bf16 v[102:105], v[154:157], v[170:173], v[102:105]
	v_mfma_f32_16x16x32_bf16 v[70:73], v[162:165], v[170:173], v[70:73]
	v_mfma_f32_16x16x32_bf16 v[114:117], v[154:157], v[178:181], v[114:117]
	v_mfma_f32_16x16x32_bf16 v[82:85], v[162:165], v[178:181], v[82:85]
	s_add_i32 m0, s61, 0x20000
	s_nop 0
	global_load_lds_dwordx4 v208, s[88:89]
	v_mfma_f32_16x16x32_bf16 v[110:113], v[154:157], v[186:189], v[110:113]
	v_mfma_f32_16x16x32_bf16 v[78:81], v[162:165], v[186:189], v[78:81]
	v_mfma_f32_16x16x32_bf16 v[106:109], v[154:157], v[194:197], v[106:109]
	v_mfma_f32_16x16x32_bf16 v[74:77], v[162:165], v[194:197], v[74:77]
	s_add_i32 m0, s61, 0x22000
	s_nop 0
	global_load_lds_dwordx4 v212, s[88:89]
	v_mfma_f32_16x16x32_bf16 v[130:133], v[134:137], v[166:169], v[130:133]
	v_mfma_f32_16x16x32_bf16 v[98:101], v[142:145], v[166:169], v[98:101]
	v_mfma_f32_16x16x32_bf16 v[126:129], v[134:137], v[174:177], v[126:129]
	v_mfma_f32_16x16x32_bf16 v[94:97], v[142:145], v[174:177], v[94:97]
	s_mov_b32 m0, s95
	s_nop 0
	global_load_lds_dwordx4 v206, s[84:85]
	v_mfma_f32_16x16x32_bf16 v[122:125], v[134:137], v[182:185], v[122:125]
	v_mfma_f32_16x16x32_bf16 v[90:93], v[142:145], v[182:185], v[90:93]
	v_mfma_f32_16x16x32_bf16 v[118:121], v[134:137], v[190:193], v[118:121]
	v_mfma_f32_16x16x32_bf16 v[86:89], v[142:145], v[190:193], v[86:89]
	s_mov_b32 m0, s96
	s_nop 0
	global_load_lds_dwordx4 v210, s[84:85]
	v_mfma_f32_16x16x32_bf16 v[130:133], v[138:141], v[170:173], v[130:133]
	v_mfma_f32_16x16x32_bf16 v[98:101], v[146:149], v[170:173], v[98:101]
	v_mfma_f32_16x16x32_bf16 v[126:129], v[138:141], v[178:181], v[126:129]
	v_mfma_f32_16x16x32_bf16 v[94:97], v[146:149], v[178:181], v[94:97]
	v_mfma_f32_16x16x32_bf16 v[122:125], v[138:141], v[186:189], v[122:125]
	v_mfma_f32_16x16x32_bf16 v[90:93], v[146:149], v[186:189], v[90:93]
	v_mfma_f32_16x16x32_bf16 v[118:121], v[138:141], v[194:197], v[118:121]
	v_mfma_f32_16x16x32_bf16 v[86:89], v[146:149], v[194:197], v[86:89]
	s_add_u32 s2, s2, 0x80
	s_addc_u32 s3, s3, 0
	s_add_u32 s84, s84, 0x80
	s_addc_u32 s85, s85, 0
	s_barrier
	s_setprio 0
	s_add_i32 s45, s45, 1
	s_cmp_lt_u32 s45, 4
	s_cbranch_scc1 .Lhu_yl
	ds_read_b128 v[150:153], v248
	ds_read_b128 v[154:157], v248 offset:1024
	ds_read_b128 v[158:161], v248 offset:2048
	ds_read_b128 v[162:165], v248 offset:3072
	ds_read_b128 v[134:137], v249
	ds_read_b128 v[138:141], v249 offset:1024
	ds_read_b128 v[142:145], v249 offset:2048
	ds_read_b128 v[146:149], v249 offset:3072
	ds_read_b128 v[166:169], v250
	ds_read_b128 v[170:173], v250 offset:1024
	ds_read_b128 v[174:177], v250 offset:2048
	ds_read_b128 v[178:181], v250 offset:3072
	ds_read_b128 v[182:185], v250 offset:4096
	ds_read_b128 v[186:189], v250 offset:5120
	ds_read_b128 v[190:193], v250 offset:6144
	ds_read_b128 v[194:197], v250 offset:7168
	s_setprio 1
	s_waitcnt vmcnt(6) lgkmcnt(0)
	s_barrier
	s_add_u32 s88, s2, 0x40000
	s_addc_u32 s89, s3, 0
	v_mfma_f32_16x16x32_bf16 v[102:105], v[150:153], v[166:169], v[102:105]
	v_mfma_f32_16x16x32_bf16 v[70:73], v[158:161], v[166:169], v[70:73]
	v_mfma_f32_16x16x32_bf16 v[114:117], v[150:153], v[174:177], v[114:117]
	v_mfma_f32_16x16x32_bf16 v[82:85], v[158:161], v[174:177], v[82:85]
	s_mov_b32 m0, s73
	s_nop 0
	global_load_lds_dwordx4 v208, s[2:3]
	v_mfma_f32_16x16x32_bf16 v[110:113], v[150:153], v[182:185], v[110:113]
	v_mfma_f32_16x16x32_bf16 v[78:81], v[158:161], v[182:185], v[78:81]
	v_mfma_f32_16x16x32_bf16 v[106:109], v[150:153], v[190:193], v[106:109]
	v_mfma_f32_16x16x32_bf16 v[74:77], v[158:161], v[190:193], v[74:77]
	s_mov_b32 m0, s75
	s_nop 0
	global_load_lds_dwordx4 v212, s[2:3]
	v_mfma_f32_16x16x32_bf16 v[102:105], v[154:157], v[170:173], v[102:105]
	v_mfma_f32_16x16x32_bf16 v[70:73], v[162:165], v[170:173], v[70:73]
	v_mfma_f32_16x16x32_bf16 v[114:117], v[154:157], v[178:181], v[114:117]
	v_mfma_f32_16x16x32_bf16 v[82:85], v[162:165], v[178:181], v[82:85]
	s_mov_b32 m0, s92
	s_nop 0
	global_load_lds_dwordx4 v208, s[88:89]
	v_mfma_f32_16x16x32_bf16 v[110:113], v[154:157], v[186:189], v[110:113]
	v_mfma_f32_16x16x32_bf16 v[78:81], v[162:165], v[186:189], v[78:81]
	v_mfma_f32_16x16x32_bf16 v[106:109], v[154:157], v[194:197], v[106:109]
	v_mfma_f32_16x16x32_bf16 v[74:77], v[162:165], v[194:197], v[74:77]
	s_mov_b32 m0, s93
	s_nop 0
	global_load_lds_dwordx4 v212, s[88:89]
	v_mfma_f32_16x16x32_bf16 v[130:133], v[134:137], v[166:169], v[130:133]
	v_mfma_f32_16x16x32_bf16 v[98:101], v[142:145], v[166:169], v[98:101]
	v_mfma_f32_16x16x32_bf16 v[126:129], v[134:137], v[174:177], v[126:129]
	v_mfma_f32_16x16x32_bf16 v[94:97], v[142:145], v[174:177], v[94:97]
	s_mov_b32 m0, s61
	s_nop 0
	global_load_lds_dwordx4 v206, s[84:85]
	v_mfma_f32_16x16x32_bf16 v[122:125], v[134:137], v[182:185], v[122:125]
	v_mfma_f32_16x16x32_bf16 v[90:93], v[142:145], v[182:185], v[90:93]
	v_mfma_f32_16x16x32_bf16 v[118:121], v[134:137], v[190:193], v[118:121]
	v_mfma_f32_16x16x32_bf16 v[86:89], v[142:145], v[190:193], v[86:89]
	s_mov_b32 m0, s94
	s_nop 0
	global_load_lds_dwordx4 v210, s[84:85]
	v_mfma_f32_16x16x32_bf16 v[130:133], v[138:141], v[170:173], v[130:133]
	v_mfma_f32_16x16x32_bf16 v[98:101], v[146:149], v[170:173], v[98:101]
	v_mfma_f32_16x16x32_bf16 v[126:129], v[138:141], v[178:181], v[126:129]
	v_mfma_f32_16x16x32_bf16 v[94:97], v[146:149], v[178:181], v[94:97]
	v_mfma_f32_16x16x32_bf16 v[122:125], v[138:141], v[186:189], v[122:125]
	v_mfma_f32_16x16x32_bf16 v[90:93], v[146:149], v[186:189], v[90:93]
	v_mfma_f32_16x16x32_bf16 v[118:121], v[138:141], v[194:197], v[118:121]
	v_mfma_f32_16x16x32_bf16 v[86:89], v[146:149], v[194:197], v[86:89]
	s_add_u32 s2, s2, 0x80
	s_addc_u32 s3, s3, 0
	s_add_u32 s84, s84, 0x80
	s_addc_u32 s85, s85, 0
	s_barrier
	s_setprio 0
	ds_read_b128 v[150:153], v220
	ds_read_b128 v[154:157], v220 offset:1024
	ds_read_b128 v[158:161], v220 offset:2048
	ds_read_b128 v[162:165], v220 offset:3072
	ds_read_b128 v[134:137], v221
	ds_read_b128 v[138:141], v221 offset:1024
	ds_read_b128 v[142:145], v221 offset:2048
	ds_read_b128 v[146:149], v221 offset:3072
	ds_read_b128 v[166:169], v250 offset:32768
	ds_read_b128 v[170:173], v250 offset:33792
	ds_read_b128 v[174:177], v250 offset:34816
	ds_read_b128 v[178:181], v250 offset:35840
	ds_read_b128 v[182:185], v250 offset:36864
	ds_read_b128 v[186:189], v250 offset:37888
	ds_read_b128 v[190:193], v250 offset:38912
	ds_read_b128 v[194:197], v250 offset:39936
	s_setprio 1
	s_waitcnt vmcnt(6) lgkmcnt(0)
	s_barrier
	v_mfma_f32_16x16x32_bf16 v[102:105], v[150:153], v[166:169], v[102:105]
	v_mfma_f32_16x16x32_bf16 v[70:73], v[158:161], v[166:169], v[70:73]
	v_mfma_f32_16x16x32_bf16 v[114:117], v[150:153], v[174:177], v[114:117]
	v_mfma_f32_16x16x32_bf16 v[82:85], v[158:161], v[174:177], v[82:85]
	v_mfma_f32_16x16x32_bf16 v[110:113], v[150:153], v[182:185], v[110:113]
	v_mfma_f32_16x16x32_bf16 v[78:81], v[158:161], v[182:185], v[78:81]
	v_mfma_f32_16x16x32_bf16 v[106:109], v[150:153], v[190:193], v[106:109]
	v_mfma_f32_16x16x32_bf16 v[74:77], v[158:161], v[190:193], v[74:77]
	v_mfma_f32_16x16x32_bf16 v[102:105], v[154:157], v[170:173], v[102:105]
	v_mfma_f32_16x16x32_bf16 v[70:73], v[162:165], v[170:173], v[70:73]
	v_mfma_f32_16x16x32_bf16 v[114:117], v[154:157], v[178:181], v[114:117]
	v_mfma_f32_16x16x32_bf16 v[82:85], v[162:165], v[178:181], v[82:85]
	v_mfma_f32_16x16x32_bf16 v[110:113], v[154:157], v[186:189], v[110:113]
	v_mfma_f32_16x16x32_bf16 v[78:81], v[162:165], v[186:189], v[78:81]
	v_mfma_f32_16x16x32_bf16 v[106:109], v[154:157], v[194:197], v[106:109]
	v_mfma_f32_16x16x32_bf16 v[74:77], v[162:165], v[194:197], v[74:77]
	v_mfma_f32_16x16x32_bf16 v[130:133], v[134:137], v[166:169], v[130:133]
	v_mfma_f32_16x16x32_bf16 v[98:101], v[142:145], v[166:169], v[98:101]
	v_mfma_f32_16x16x32_bf16 v[126:129], v[134:137], v[174:177], v[126:129]
	v_mfma_f32_16x16x32_bf16 v[94:97], v[142:145], v[174:177], v[94:97]
	v_mfma_f32_16x16x32_bf16 v[122:125], v[134:137], v[182:185], v[122:125]
	v_mfma_f32_16x16x32_bf16 v[90:93], v[142:145], v[182:185], v[90:93]
	v_mfma_f32_16x16x32_bf16 v[118:121], v[134:137], v[190:193], v[118:121]
	v_mfma_f32_16x16x32_bf16 v[86:89], v[142:145], v[190:193], v[86:89]
	v_mfma_f32_16x16x32_bf16 v[130:133], v[138:141], v[170:173], v[130:133]
	v_mfma_f32_16x16x32_bf16 v[98:101], v[146:149], v[170:173], v[98:101]
	v_mfma_f32_16x16x32_bf16 v[126:129], v[138:141], v[178:181], v[126:129]
	v_mfma_f32_16x16x32_bf16 v[94:97], v[146:149], v[178:181], v[94:97]
	v_mfma_f32_16x16x32_bf16 v[122:125], v[138:141], v[186:189], v[122:125]
	v_mfma_f32_16x16x32_bf16 v[90:93], v[146:149], v[186:189], v[90:93]
	v_mfma_f32_16x16x32_bf16 v[118:121], v[138:141], v[194:197], v[118:121]
	v_mfma_f32_16x16x32_bf16 v[86:89], v[146:149], v[194:197], v[86:89]
	s_barrier
	s_setprio 0
	ds_read_b128 v[150:153], v222
	ds_read_b128 v[154:157], v222 offset:1024
	ds_read_b128 v[158:161], v222 offset:2048
	ds_read_b128 v[162:165], v222 offset:3072
	ds_read_b128 v[134:137], v223
	ds_read_b128 v[138:141], v223 offset:1024
	ds_read_b128 v[142:145], v223 offset:2048
	ds_read_b128 v[146:149], v223 offset:3072
	ds_read_b128 v[166:169], v250 offset:16384
	ds_read_b128 v[170:173], v250 offset:17408
	ds_read_b128 v[174:177], v250 offset:18432
	ds_read_b128 v[178:181], v250 offset:19456
	ds_read_b128 v[182:185], v250 offset:20480
	ds_read_b128 v[186:189], v250 offset:21504
	ds_read_b128 v[190:193], v250 offset:22528
	ds_read_b128 v[194:197], v250 offset:23552
	s_setprio 1
	s_waitcnt vmcnt(0) lgkmcnt(0)
	s_barrier
	v_mfma_f32_16x16x32_bf16 v[102:105], v[150:153], v[166:169], v[102:105]
	v_mfma_f32_16x16x32_bf16 v[70:73], v[158:161], v[166:169], v[70:73]
	v_mfma_f32_16x16x32_bf16 v[114:117], v[150:153], v[174:177], v[114:117]
	v_mfma_f32_16x16x32_bf16 v[82:85], v[158:161], v[174:177], v[82:85]
	v_mfma_f32_16x16x32_bf16 v[110:113], v[150:153], v[182:185], v[110:113]
	v_mfma_f32_16x16x32_bf16 v[78:81], v[158:161], v[182:185], v[78:81]
	v_mfma_f32_16x16x32_bf16 v[106:109], v[150:153], v[190:193], v[106:109]
	v_mfma_f32_16x16x32_bf16 v[74:77], v[158:161], v[190:193], v[74:77]
	v_mfma_f32_16x16x32_bf16 v[102:105], v[154:157], v[170:173], v[102:105]
	v_mfma_f32_16x16x32_bf16 v[70:73], v[162:165], v[170:173], v[70:73]
	v_mfma_f32_16x16x32_bf16 v[114:117], v[154:157], v[178:181], v[114:117]
	v_mfma_f32_16x16x32_bf16 v[82:85], v[162:165], v[178:181], v[82:85]
	v_mfma_f32_16x16x32_bf16 v[110:113], v[154:157], v[186:189], v[110:113]
	v_mfma_f32_16x16x32_bf16 v[78:81], v[162:165], v[186:189], v[78:81]
	v_mfma_f32_16x16x32_bf16 v[106:109], v[154:157], v[194:197], v[106:109]
	v_mfma_f32_16x16x32_bf16 v[74:77], v[162:165], v[194:197], v[74:77]
	v_mfma_f32_16x16x32_bf16 v[130:133], v[134:137], v[166:169], v[130:133]
	v_mfma_f32_16x16x32_bf16 v[98:101], v[142:145], v[166:169], v[98:101]
	v_mfma_f32_16x16x32_bf16 v[126:129], v[134:137], v[174:177], v[126:129]
	v_mfma_f32_16x16x32_bf16 v[94:97], v[142:145], v[174:177], v[94:97]
	v_mfma_f32_16x16x32_bf16 v[122:125], v[134:137], v[182:185], v[122:125]
	v_mfma_f32_16x16x32_bf16 v[90:93], v[142:145], v[182:185], v[90:93]
	v_mfma_f32_16x16x32_bf16 v[118:121], v[134:137], v[190:193], v[118:121]
	v_mfma_f32_16x16x32_bf16 v[86:89], v[142:145], v[190:193], v[86:89]
	v_mfma_f32_16x16x32_bf16 v[130:133], v[138:141], v[170:173], v[130:133]
	v_mfma_f32_16x16x32_bf16 v[98:101], v[146:149], v[170:173], v[98:101]
	v_mfma_f32_16x16x32_bf16 v[126:129], v[138:141], v[178:181], v[126:129]
	v_mfma_f32_16x16x32_bf16 v[94:97], v[146:149], v[178:181], v[94:97]
	v_mfma_f32_16x16x32_bf16 v[122:125], v[138:141], v[186:189], v[122:125]
	v_mfma_f32_16x16x32_bf16 v[90:93], v[146:149], v[186:189], v[90:93]
	v_mfma_f32_16x16x32_bf16 v[118:121], v[138:141], v[194:197], v[118:121]
	v_mfma_f32_16x16x32_bf16 v[86:89], v[146:149], v[194:197], v[86:89]
	s_barrier
	s_setprio 0
	ds_read_b128 v[150:153], v248
	ds_read_b128 v[154:157], v248 offset:1024
	ds_read_b128 v[158:161], v248 offset:2048
	ds_read_b128 v[162:165], v248 offset:3072
	ds_read_b128 v[134:137], v249
	ds_read_b128 v[138:141], v249 offset:1024
	ds_read_b128 v[142:145], v249 offset:2048
	ds_read_b128 v[146:149], v249 offset:3072
	ds_read_b128 v[166:169], v250
	ds_read_b128 v[170:173], v250 offset:1024
	ds_read_b128 v[174:177], v250 offset:2048
	ds_read_b128 v[178:181], v250 offset:3072
	ds_read_b128 v[182:185], v250 offset:4096
	ds_read_b128 v[186:189], v250 offset:5120
	ds_read_b128 v[190:193], v250 offset:6144
	ds_read_b128 v[194:197], v250 offset:7168
	s_setprio 1
	s_waitcnt vmcnt(0) lgkmcnt(0)
	s_barrier
	v_mfma_f32_16x16x32_bf16 v[102:105], v[150:153], v[166:169], v[102:105]
	v_mfma_f32_16x16x32_bf16 v[70:73], v[158:161], v[166:169], v[70:73]
	v_mfma_f32_16x16x32_bf16 v[114:117], v[150:153], v[174:177], v[114:117]
	v_mfma_f32_16x16x32_bf16 v[82:85], v[158:161], v[174:177], v[82:85]
	v_mfma_f32_16x16x32_bf16 v[110:113], v[150:153], v[182:185], v[110:113]
	v_mfma_f32_16x16x32_bf16 v[78:81], v[158:161], v[182:185], v[78:81]
	v_mfma_f32_16x16x32_bf16 v[106:109], v[150:153], v[190:193], v[106:109]
	v_mfma_f32_16x16x32_bf16 v[74:77], v[158:161], v[190:193], v[74:77]
	v_mfma_f32_16x16x32_bf16 v[102:105], v[154:157], v[170:173], v[102:105]
	v_mfma_f32_16x16x32_bf16 v[70:73], v[162:165], v[170:173], v[70:73]
	v_mfma_f32_16x16x32_bf16 v[114:117], v[154:157], v[178:181], v[114:117]
	v_mfma_f32_16x16x32_bf16 v[82:85], v[162:165], v[178:181], v[82:85]
	v_mfma_f32_16x16x32_bf16 v[110:113], v[154:157], v[186:189], v[110:113]
	v_mfma_f32_16x16x32_bf16 v[78:81], v[162:165], v[186:189], v[78:81]
	v_mfma_f32_16x16x32_bf16 v[106:109], v[154:157], v[194:197], v[106:109]
	v_mfma_f32_16x16x32_bf16 v[74:77], v[162:165], v[194:197], v[74:77]
	v_mfma_f32_16x16x32_bf16 v[130:133], v[134:137], v[166:169], v[130:133]
	v_mfma_f32_16x16x32_bf16 v[98:101], v[142:145], v[166:169], v[98:101]
	v_mfma_f32_16x16x32_bf16 v[126:129], v[134:137], v[174:177], v[126:129]
	v_mfma_f32_16x16x32_bf16 v[94:97], v[142:145], v[174:177], v[94:97]
	v_mfma_f32_16x16x32_bf16 v[122:125], v[134:137], v[182:185], v[122:125]
	v_mfma_f32_16x16x32_bf16 v[90:93], v[142:145], v[182:185], v[90:93]
	v_mfma_f32_16x16x32_bf16 v[118:121], v[134:137], v[190:193], v[118:121]
	v_mfma_f32_16x16x32_bf16 v[86:89], v[142:145], v[190:193], v[86:89]
	v_mfma_f32_16x16x32_bf16 v[130:133], v[138:141], v[170:173], v[130:133]
	v_mfma_f32_16x16x32_bf16 v[98:101], v[146:149], v[170:173], v[98:101]
	v_mfma_f32_16x16x32_bf16 v[126:129], v[138:141], v[178:181], v[126:129]
	v_mfma_f32_16x16x32_bf16 v[94:97], v[146:149], v[178:181], v[94:97]
	v_mfma_f32_16x16x32_bf16 v[122:125], v[138:141], v[186:189], v[122:125]
	v_mfma_f32_16x16x32_bf16 v[90:93], v[146:149], v[186:189], v[90:93]
	v_mfma_f32_16x16x32_bf16 v[118:121], v[138:141], v[194:197], v[118:121]
	v_mfma_f32_16x16x32_bf16 v[86:89], v[146:149], v[194:197], v[86:89]
	s_barrier
	s_setprio 0
	s_mov_b64 s[0:1], -1
	s_branch .LBB0_122
